# v057 + ff1 column panels processed in descending order so the hidden-buffer columns ff2 reads first are the most recently written
# baseline (speedup 1.0000x reference)
.LBB0_368:
	s_lshl_b32 s20, s85, 3
	v_cvt_f32_u32_e32 v0, s20
	s_sub_i32 s29, 0, s20
	s_ashr_i32 s6, s6, 3
	s_add_i32 s6, s27, s6
	v_rcp_iflag_f32_e32 v0, v0
	s_abs_i32 s27, s6
	s_ashr_i32 s26, s6, 31
	v_mul_f32_e32 v0, 0x4f7ffffe, v0
	v_cvt_u32_f32_e32 v0, v0
	s_nop 0
	v_readfirstlane_b32 s31, v0
	s_mul_i32 s29, s29, s31
	s_mul_hi_u32 s29, s31, s29
	s_add_i32 s31, s31, s29
	s_mul_hi_u32 s29, s27, s31
	s_mul_i32 s31, s29, s20
	s_sub_i32 s27, s27, s31
	s_add_i32 s31, s29, 1
	s_sub_i32 s38, s27, s20
	s_cmp_ge_u32 s27, s20
	s_cselect_b32 s29, s31, s29
	s_cselect_b32 s27, s38, s27
	s_add_i32 s31, s29, 1
	s_cmp_ge_u32 s27, s20
	s_cselect_b32 s27, s31, s29
	s_xor_b32 s27, s27, s26
	s_sub_i32 s26, s27, s26
	s_lshl_b32 s27, s26, 3
	s_sub_i32 s29, s92, s27
	s_min_i32 s29, s29, 8
	s_abs_i32 s31, s29
	v_cvt_f32_u32_e32 v0, s31
	s_sub_i32 s38, 0, s31
	s_mul_i32 s26, s26, s20
	s_sub_i32 s20, s6, s26
	v_rcp_iflag_f32_e32 v0, v0
	s_abs_i32 s26, s20
	s_xor_b32 s6, s20, s29
	s_ashr_i32 s6, s6, 31
	v_mul_f32_e32 v0, 0x4f7ffffe, v0
	v_cvt_u32_f32_e32 v0, v0
	s_nop 0
	v_readfirstlane_b32 s39, v0
	s_mul_i32 s38, s38, s39
	s_mul_hi_u32 s38, s39, s38
	s_add_i32 s39, s39, s38
	s_mul_hi_u32 s38, s26, s39
	v_cvt_f32_ubyte0_e32 v0, s88
	s_mul_i32 s39, s38, s31
	v_rcp_iflag_f32_e32 v0, v0
	s_sub_i32 s26, s26, s39
	s_add_i32 s39, s38, 1
	s_sub_i32 s42, s26, s31
	s_cmp_ge_u32 s26, s31
	s_cselect_b32 s38, s39, s38
	v_mul_f32_e32 v0, 0x4f7ffffe, v0
	s_cselect_b32 s26, s42, s26
	s_add_i32 s39, s38, 1
	v_cvt_u32_f32_e32 v0, v0
	s_cmp_ge_u32 s26, s31
	s_cselect_b32 s26, s39, s38
	s_xor_b32 s26, s26, s6
	s_sub_i32 s6, s26, s6
	v_readfirstlane_b32 s31, v0
	v_cvt_f32_u32_e32 v0, s85
	s_mul_i32 s26, s6, s29
	s_sub_i32 s29, 0, s88
	s_mul_i32 s29, s29, s31
	s_sub_i32 s20, s20, s26
	s_mul_hi_u32 s29, s31, s29
	s_add_i32 s20, s20, s27
	s_abs_i32 s27, s2
	s_add_i32 s31, s31, s29
	v_rcp_iflag_f32_e32 v0, v0
	s_mul_hi_u32 s29, s27, s31
	s_mul_i32 s31, s29, s88
	s_sub_i32 s27, s27, s31
	s_ashr_i32 s26, s2, 31
	s_add_i32 s31, s29, 1
	s_sub_i32 s38, s27, s88
	v_mul_f32_e32 v0, 0x4f7ffffe, v0
	s_cmp_ge_u32 s27, s88
	v_cvt_u32_f32_e32 v0, v0
	s_cselect_b32 s29, s31, s29
	s_cselect_b32 s27, s38, s27
	s_add_i32 s31, s29, 1
	s_cmp_ge_u32 s27, s88
	s_cselect_b32 s27, s31, s29
	s_sub_i32 s31, 0, s85
	v_readfirstlane_b32 s38, v0
	s_xor_b32 s27, s27, s26
	s_mul_i32 s31, s31, s38
	s_sub_i32 s26, s27, s26
	s_mul_hi_u32 s31, s38, s31
	s_abs_i32 s29, s26
	s_add_i32 s38, s38, s31
	s_mul_hi_u32 s31, s29, s38
	s_mul_i32 s38, s31, s85
	s_sub_i32 s29, s29, s38
	s_ashr_i32 s27, s26, 31
	s_add_i32 s38, s31, 1
	s_sub_i32 s39, s29, s85
	s_cmp_ge_u32 s29, s85
	s_cselect_b32 s31, s38, s31
	s_cselect_b32 s29, s39, s29
	s_add_i32 s38, s31, 1
	s_cmp_ge_u32 s29, s85
	s_cselect_b32 s29, s38, s31
	s_xor_b32 s29, s29, s27
	s_sub_i32 s27, s29, s27
	s_add_i32 s29, s27, s89
	s_mul_i32 s27, s27, s85
	s_sub_i32 s31, s26, s27
	s_mul_i32 s26, s26, s88
	s_sub_i32 s2, s2, s26
	s_mul_i32 s2, s90, s2
	s_lshl_b32 s2, s2, 6
	s_and_b64 s[26:27], s[36:37], exec
	v_readlane_b32 s38, v254, 58
	s_cselect_b32 s77, s20, s29
	s_cselect_b32 s76, s6, s31
	s_cselect_b32 s42, 0, s2
	s_cselect_b32 s6, s93, s90
	v_readlane_b32 s39, v254, 59
	s_cmp_eq_u32 s12, 7
	s_cbranch_scc1 .Lmo_0f
	s_cmp_eq_u32 s12, 15
	s_cbranch_scc0 .Lmo_0g
.Lmo_0f:
	s_sub_i32 s76, 31, s76
.Lmo_0g:
	s_cmp_eq_u32 s12, 8
	s_cbranch_scc0 .Lmo_0
	s_xor_b32 s77, s77, 8

.LBB0_381:
	s_ashr_i32 s3, s3, 3
	s_add_i32 s3, s57, s3
	s_abs_i32 s57, s3
	s_mul_hi_u32 s70, s57, s78
	s_mul_i32 s71, s70, s2
	s_sub_i32 s57, s57, s71
	s_ashr_i32 s7, s3, 31
	s_add_i32 s71, s70, 1
	s_sub_i32 s72, s57, s2
	s_cmp_ge_u32 s57, s2
	s_cselect_b32 s70, s71, s70
	s_cselect_b32 s57, s72, s57
	s_add_i32 s71, s70, 1
	s_cmp_ge_u32 s57, s2
	s_cselect_b32 s57, s71, s70
	s_xor_b32 s57, s57, s7
	s_sub_i32 s7, s57, s7
	s_lshl_b32 s57, s7, 3
	s_sub_i32 s70, s92, s57
	s_min_i32 s70, s70, 8
	s_abs_i32 s71, s70
	v_cvt_f32_u32_e32 v0, s71
	s_sub_i32 s73, 0, s71
	s_mul_i32 s7, s7, s2
	s_sub_i32 s3, s3, s7
	v_rcp_iflag_f32_e32 v0, v0
	s_abs_i32 s7, s3
	s_xor_b32 s72, s3, s70
	s_ashr_i32 s72, s72, 31
	v_mul_f32_e32 v0, 0x4f7ffffe, v0
	v_cvt_u32_f32_e32 v0, v0
	s_nop 0
	v_readfirstlane_b32 s74, v0
	s_mul_i32 s73, s73, s74
	s_mul_hi_u32 s73, s74, s73
	s_add_i32 s74, s74, s73
	s_mul_hi_u32 s73, s7, s74
	s_mul_i32 s74, s73, s71
	s_sub_i32 s7, s7, s74
	s_add_i32 s74, s73, 1
	s_sub_i32 s75, s7, s71
	s_cmp_ge_u32 s7, s71
	s_cselect_b32 s73, s74, s73
	s_cselect_b32 s7, s75, s7
	s_add_i32 s74, s73, 1
	s_cmp_ge_u32 s7, s71
	s_cselect_b32 s7, s74, s73
	s_xor_b32 s7, s7, s72
	s_sub_i32 s7, s7, s72
	s_mul_i32 s70, s7, s70
	s_sub_i32 s3, s3, s70
	s_abs_i32 s70, s43
	s_mul_hi_u32 s71, s70, s30
	s_mul_i32 s72, s71, s88
	s_sub_i32 s70, s70, s72
	s_add_i32 s3, s3, s57
	s_ashr_i32 s57, s43, 31
	s_add_i32 s72, s71, 1
	s_sub_i32 s73, s70, s88
	s_cmp_ge_u32 s70, s88
	s_cselect_b32 s71, s72, s71
	s_cselect_b32 s70, s73, s70
	s_add_i32 s72, s71, 1
	s_cmp_ge_u32 s70, s88
	s_cselect_b32 s70, s72, s71
	s_xor_b32 s70, s70, s57
	s_sub_i32 s57, s70, s57
	s_abs_i32 s71, s57
	s_mul_hi_u32 s72, s71, s31
	s_mul_i32 s73, s72, s85
	s_sub_i32 s71, s71, s73
	s_ashr_i32 s70, s57, 31
	s_add_i32 s73, s72, 1
	s_sub_i32 s74, s71, s85
	s_cmp_ge_u32 s71, s85
	s_cselect_b32 s72, s73, s72
	s_cselect_b32 s71, s74, s71
	s_add_i32 s73, s72, 1
	s_cmp_ge_u32 s71, s85
	s_cselect_b32 s71, s73, s72
	s_xor_b32 s71, s71, s70
	s_sub_i32 s70, s71, s70
	s_add_i32 s71, s70, s89
	s_mul_i32 s70, s70, s85
	s_sub_i32 s70, s57, s70
	s_mul_i32 s57, s57, s88
	s_sub_i32 s43, s43, s57
	v_readlane_b32 s57, v252, 9
	s_mul_i32 s43, s57, s43
	s_and_b64 s[0:1], s[0:1], exec
	s_cselect_b32 s57, s3, s71
	s_cselect_b32 s7, s7, s70
	s_cselect_b32 s70, 0, s43
	s_cselect_b32 s3, s93, s90
	s_cbranch_scc0 .Lmo_1
	s_cmp_eq_u32 s12, 7
	s_cbranch_scc1 .Lmo_1f
	s_cmp_eq_u32 s12, 15
	s_cbranch_scc0 .Lmo_1g
.Lmo_1f:
	s_sub_i32 s7, 31, s7
.Lmo_1g:
	s_cmp_eq_u32 s12, 8
	s_cbranch_scc0 .Lmo_1
	s_xor_b32 s57, s57, 8
